# v81 + mlstm_out prologue: compiler's vmcnt(0) before the last gate load removed (address temp renamed) + first grid-barrier counter scan with 16 loads in flight
# speedup vs baseline: 1.0045x; 1.0045x over previous
; #define LAS __attribute__((address_space(3)))
; DI void mlstm_out_item(const KP& P, int layer, int b, int tb, LAS unsigned char* lds) {
;     ...
;     { u32x4 qv[4], kv[4], vv[4];
; #pragma unroll
;       for (int i = 0; i < 4; ++i) { const int q = tid + 512 * i, row = q >> 5, ch = q & 31; const bf16_t* zr = Z + (R0 + row) * ZW + ch * 8;
;           qv[i] = ldg16(zr + C_QD); kv[i] = ldg16(zr + C_KD); vv[i] = ldg16(zr + C_VD); }
;       f32x4 gv = {0.f, 0.f, 0.f, 0.f};
;       if (tid < 128) gv = *(const f32x4*)(FG + R0 * 8 + tid * 4); else if (tid < 256) gv = *(const f32x4*)(IG + R0 * 8 + (tid - 128) * 4);
; #pragma unroll
;       for (int i = 0; i < 4; ++i) { const int q = tid + 512 * i, row = q >> 5, ch = q & 31;
;           *(LAS u32x4*)(Qt + row * QP + ch * 8) = qv[i]; *(LAS u32x4*)(Kt + row * QP + ch * 8) = kv[i]; *(LAS u32x4*)(Vt + row * VP + ch * 8) = vv[i]; }
;       if (tid < 256) *(LAS f32x4*)(Fs + tid * 4) = gv; }
.LBB0_540:
	s_andn2_saveexec_b64 s[0:1], s[0:1]
	s_cbranch_execz .LBB0_542
	v_readlane_b32 s2, v255, 6
	v_readlane_b32 s3, v255, 7
	s_lshl_b64 s[2:3], s[2:3], 5
	v_readlane_b32 s6, v253, 29
	v_readlane_b32 s7, v253, 30
	s_add_u32 s2, s6, s2
	s_nop 0
	v_lshlrev_b32_e32 v70, 2, v62
	s_addc_u32 s3, s7, s3
	v_ashrrev_i32_e32 v71, 31, v70
	v_lshl_add_u64 v[70:71], v[70:71], 2, s[2:3]
	global_load_dwordx4 v[48:51], v[70:71], off
